# attention loop: static s_setprio 1 for waves 0-3 (older half) on top of VALU diet
# speedup vs baseline: 1.0044x; 1.0016x over previous
; #define WAIT_BAR(N) asm volatile("s_waitcnt vmcnt(" #N ") lgkmcnt(0)\n\ts_barrier":::"memory")
;   #define DMA_K(t,slot) glds16(ksrc+(long)(t)*KVBLK*DM,(unsigned)__builtin_amdgcn_readfirstlane(kdst+(slot)))
;   #define DMA_V(t,slot) do{ glds16(vsrc+(long)(t)*KVBLK*DM,(unsigned)__builtin_amdgcn_readfirstlane(vdst+2*(slot))); glds16(vsrc+(long)(t)*KVBLK*DM+64,(unsigned)__builtin_amdgcn_readfirstlane(vdst+2*(slot)+8192)); }while(0)
;   #define CMASK(P0,P1,t) do{int jb_=(t)-(NT-4); if(jb_>=0)cmask(P0,P1,jb_,qrel,hi);}while(0)
;   #define ROT() do{sl_prev=sl_cur;sl_cur=sl_next;sl_next=(sl_next==(NSLOT-1)*SLOTB)?0:sl_next+SLOTB;}while(0)
;   #define CMASK(P0,P1,t) do{}while(0)
;   #define CMASK(P0,P1,t) do{int jb_=(t)-(NT-4); if(jb_>=0)cmask(P0,P1,jb_,qrel,hi);}while(0)
; template<int DUMMY> __device__ __forceinline__ void attn_pass2(const bf16*Qh,const bf16*__restrict__ Kh,const bf16*__restrict__ Vh,const int q0,char*shm,f32x16 (&o)[4]){
;     ...
;   const lds_cptr shm3=(lds_cptr)shm; const lds_cptr kp0=shm3+L2_K+hi*1024+r32*16; const lds_cptr vp0=shm3+L2_V+((lane>>4)&1)*32+(lane&3)*8+(4*hi+((lane&15)>>2))*64;
;   const int NT=(q0+QB)/KVBLK;
;   DMA_K(0,0);DMA_V(0,0);DMA_K(1,SLOTB);
;   bf16x8 qr[4];
;   #pragma unroll
;   for(int d0=0;d0<4;++d0)qr[d0]=*reinterpret_cast<const bf16x8*>(&Qw[(long)r32*DM+d0*16+hi*8]);
;   float l_reg=0.f;o[0]=f32x16{};o[1]=f32x16{};o[2]=f32x16{};o[3]=f32x16{};
;   const f32x16 zero16=f32x16{};
;   const int qrel=wid*QBLK+r32;
;     ...
;   f32x16 pA0,pA1,pB0,pB1;
;   int sl_prev=0,sl_cur=0,sl_next=SLOTB;
;     ...
;   DMA_K(2,2*SLOTB);
;   WAIT_BAR(4);
;   qkt(pA0,pA1,Kbase,qr,zero16,r32,hi);CMASK(pA0,pA1,0);
;   _Pragma("unroll") for(int r=0;r<16;++r){pA0[r]=__builtin_amdgcn_exp2f(pA0[r]);pA1[r]=__builtin_amdgcn_exp2f(pA1[r]);}
;   WAIT_BAR(0);
;   DMA_K(3,0);DMA_V(1,SLOTB);
;   ROT();
;   kload8(kf,kp0+sl_cur);
;   WAIT_BAR(3);
;   s16x4 vlo[8],vhi[8]; u32x4 pw0,pw1,pw2,pw3;
.LBB0_302:
	s_waitcnt vmcnt(0) lgkmcnt(0)
	s_barrier
	s_ashr_i32 s25, s14, 6
	s_nop 7
	v_exp_f32_e32 v96, v0
	v_exp_f32_e32 v97, v1
	v_lshl_add_u64 v[0:1], v[208:209], 0, s[42:43]
	s_mov_b32 s14, m0
	s_mov_b32 m0, s20
	s_nop 0
	global_load_lds_dwordx4 v[0:1], off
	s_mov_b32 m0, s14
	s_mov_b64 s[14:15], 0x60000
	s_cmp_lg_u32 0, -1
	v_lshl_add_u64 v[0:1], v[32:33], 0, s[14:15]
	s_cselect_b32 s14, 0, 0
	s_add_i32 s11, s14, s11
	s_add_i32 s14, s11, 0xa000
	s_mov_b32 s15, m0
	s_mov_b32 m0, s14
	s_nop 0
	global_load_lds_dwordx4 v[0:1], off
	s_mov_b32 m0, s15
	s_mov_b64 s[14:15], 0x60080
	v_lshl_add_u64 v[0:1], v[32:33], 0, s[14:15]
	s_add_i32 s11, s11, 0xc000
	s_mov_b32 s14, m0
	s_mov_b32 m0, s11
	s_nop 0
	global_load_lds_dwordx4 v[0:1], off
	s_mov_b32 m0, s14
	ds_read_b128 v[204:207], v241 offset:8192
	ds_read_b128 v[200:203], v241 offset:8704
	ds_read_b128 v[196:199], v241 offset:10240
	ds_read_b128 v[192:195], v241 offset:10752
	ds_read_b128 v[188:191], v241 offset:12288
	ds_read_b128 v[184:187], v241 offset:12800
	ds_read_b128 v[180:183], v241 offset:14336
	ds_read_b128 v[176:179], v241 offset:14848
	v_lshlrev_b32_e32 v36, 1, v34
	v_exp_f32_e32 v80, v16
	v_exp_f32_e32 v81, v17
	v_exp_f32_e32 v98, v2
	v_exp_f32_e32 v82, v18
	v_exp_f32_e32 v99, v3
	v_exp_f32_e32 v83, v19
	v_exp_f32_e32 v100, v4
	v_exp_f32_e32 v84, v20
	v_exp_f32_e32 v101, v5
	v_exp_f32_e32 v85, v21
	v_exp_f32_e32 v102, v6
	v_exp_f32_e32 v86, v22
	v_exp_f32_e32 v103, v7
	v_exp_f32_e32 v87, v23
	v_exp_f32_e32 v104, v8
	v_exp_f32_e32 v88, v24
	v_exp_f32_e32 v105, v9
	v_exp_f32_e32 v89, v25
	v_exp_f32_e32 v106, v10
	v_exp_f32_e32 v90, v26
	v_exp_f32_e32 v107, v11
	v_exp_f32_e32 v91, v27
	v_exp_f32_e32 v108, v12
	v_exp_f32_e32 v92, v28
	v_exp_f32_e32 v109, v13
	v_exp_f32_e32 v93, v29
	v_exp_f32_e32 v110, v14
	v_exp_f32_e32 v94, v30
	v_exp_f32_e32 v111, v15
	v_exp_f32_e32 v95, v31
	v_and_b32_e32 v36, 32, v36
	v_lshlrev_b32_e32 v37, 4, v34
	s_waitcnt vmcnt(3) lgkmcnt(0)
	s_barrier
	v_add3_u32 v35, 0, v36, v35
	v_lshlrev_b32_e32 v36, 8, v214
	v_and_b32_e32 v37, 0xc0, v37
	v_and_b32_e32 v0, 3, v34
	s_mov_b32 s35, 1
	v_add3_u32 v239, v35, v36, v37
	s_mov_b32 s37, 0
	s_mov_b32 s15, 0
	s_cmp_lt_i32 s2, 1
	v_lshlrev_b32_e32 v210, 4, v0
	s_cbranch_scc1 .LBB0_314
	s_add_i32 s11, s25, -5
	s_lshl_b64 s[26:27], s[54:55], 1
	s_add_u32 s14, s12, s26
	s_addc_u32 s24, s13, s27
	s_add_u32 s26, s14, s31
	v_mov_b32_e32 v211, v213
	s_addc_u32 s27, s24, s29
	v_lshl_add_u64 v[0:1], s[26:27], 0, v[210:211]
	v_lshl_add_u64 v[0:1], v[0:1], 0, v[212:213]
	v_mov_b32_e32 v64, 0
	v_lshl_add_u64 v[66:67], s[6:7], 0, v[0:1]
	s_movk_i32 s28, 0x4000
	s_movk_i32 s27, 0x2000
	s_mov_b64 s[56:57], 0
	v_mov_b32_e32 v0, 0
	v_mov_b32_e32 v1, v64
	v_mov_b32_e32 v2, v64
	v_mov_b32_e32 v3, v64
	v_mov_b32_e32 v4, v64
	v_mov_b32_e32 v5, v64
	v_mov_b32_e32 v6, v64
	v_mov_b32_e32 v7, v64
	v_mov_b32_e32 v8, v64
	v_mov_b32_e32 v9, v64
	v_mov_b32_e32 v10, v64
	v_mov_b32_e32 v11, v64
	v_mov_b32_e32 v12, v64
	v_mov_b32_e32 v13, v64
	v_mov_b32_e32 v14, v64
	v_mov_b32_e32 v15, v64
	v_mov_b32_e32 v16, 0
	v_mov_b32_e32 v17, v64
	v_mov_b32_e32 v18, v64
	v_mov_b32_e32 v19, v64
	v_mov_b32_e32 v20, v64
	v_mov_b32_e32 v21, v64
	v_mov_b32_e32 v22, v64
	v_mov_b32_e32 v23, v64
	v_mov_b32_e32 v24, v64
	v_mov_b32_e32 v25, v64
	v_mov_b32_e32 v26, v64
	v_mov_b32_e32 v27, v64
	v_mov_b32_e32 v28, v64
	v_mov_b32_e32 v29, v64
	v_mov_b32_e32 v30, v64
	v_mov_b32_e32 v31, v64
	v_mov_b32_e32 v32, 0
	v_mov_b32_e32 v33, v64
	v_mov_b32_e32 v34, v64
	v_mov_b32_e32 v35, v64
	v_mov_b32_e32 v36, v64
	v_mov_b32_e32 v37, v64
	v_mov_b32_e32 v38, v64
	v_mov_b32_e32 v39, v64
	v_mov_b32_e32 v40, v64
	v_mov_b32_e32 v41, v64
	v_mov_b32_e32 v42, v64
	v_mov_b32_e32 v43, v64
	v_mov_b32_e32 v44, v64
	v_mov_b32_e32 v45, v64
	v_mov_b32_e32 v46, v64
	v_mov_b32_e32 v47, v64
	v_mov_b32_e32 v48, 0
	v_mov_b32_e32 v49, v64
	v_mov_b32_e32 v50, v64
	v_mov_b32_e32 v51, v64
	v_mov_b32_e32 v52, v64
	v_mov_b32_e32 v53, v64
	v_mov_b32_e32 v54, v64
	v_mov_b32_e32 v55, v64
	v_mov_b32_e32 v56, v64
	v_mov_b32_e32 v57, v64
	v_mov_b32_e32 v58, v64
	v_mov_b32_e32 v59, v64
	v_mov_b32_e32 v60, v64
	v_mov_b32_e32 v61, v64
	v_mov_b32_e32 v62, v64
	v_mov_b32_e32 v63, v64
	s_cmp_ge_u32 s18, 0x100
	s_cbranch_scc1 .Lattn_prio_skip
	s_setprio 1
.Lattn_prio_skip:
	v_readfirstlane_b32 s98, v208
	v_readfirstlane_b32 s99, v209
	v_readfirstlane_b32 s100, v66
	v_readfirstlane_b32 s101, v67
	v_subrev_u32_e32 v250, s98, v208
	v_subrev_u32_e32 v251, s100, v66
	s_add_u32 s98, s98, 0x180000
	s_addc_u32 s99, s99, 0
	s_add_u32 s100, s100, 0x100c1000
	s_addc_u32 s101, s101, 0
.LBB0_304:
	s_mov_b32 s37, s28
	s_mov_b32 s14, s27
	v_lshl_add_u32 v65, s15, 1, v239
	ds_read_b64_tr_b16 v[72:73], v65 offset:24576
	ds_read_b64_tr_b16 v[74:75], v65 offset:25088
	v_add_f32_e32 v68, v96, v97
	v_add_f32_e32 v68, v98, v68
	v_add_f32_e32 v68, v99, v68
	v_add_f32_e32 v68, v100, v68
	v_add_f32_e32 v68, v101, v68
	v_cvt_pk_bf16_f32 v172, v96, v97
	v_cvt_pk_bf16_f32 v173, v98, v99
	s_waitcnt lgkmcnt(9)
	v_mfma_f32_32x32x16_bf16 v[128:143], v[204:207], v[168:171], 0
	ds_read_b64_tr_b16 v[76:77], v65 offset:28672
	ds_read_b64_tr_b16 v[78:79], v65 offset:29184
	v_add_f32_e32 v68, v102, v68
	v_add_f32_e32 v68, v103, v68
	v_add_f32_e32 v68, v104, v68
	v_add_f32_e32 v68, v105, v68
	v_cvt_pk_bf16_f32 v174, v100, v101
	v_cvt_pk_bf16_f32 v175, v102, v103
	s_waitcnt lgkmcnt(10)
	v_mfma_f32_32x32x16_bf16 v[112:127], v[200:203], v[168:171], 0
	ds_read_b64_tr_b16 v[96:97], v65 offset:32768
	ds_read_b64_tr_b16 v[98:99], v65 offset:33280
	v_add_f32_e32 v68, v106, v68
	v_add_f32_e32 v68, v107, v68
	v_add_f32_e32 v68, v108, v68
	v_add_f32_e32 v68, v109, v68
	v_cvt_pk_bf16_f32 v164, v104, v105
	v_cvt_pk_bf16_f32 v165, v106, v107
	s_waitcnt lgkmcnt(11)
	v_mfma_f32_32x32x16_bf16 v[128:143], v[196:199], v[160:163], v[128:143]
	ds_read_b64_tr_b16 v[100:101], v65 offset:36864
	ds_read_b64_tr_b16 v[102:103], v65 offset:37376
	v_add_f32_e32 v68, v110, v68
	v_add_f32_e32 v68, v111, v68
	v_add_f32_e32 v68, v80, v68
	v_add_f32_e32 v68, v81, v68
	v_cvt_pk_bf16_f32 v166, v108, v109
	v_cvt_pk_bf16_f32 v167, v110, v111
	s_waitcnt lgkmcnt(12)
	v_mfma_f32_32x32x16_bf16 v[112:127], v[192:195], v[160:163], v[112:127]
	ds_read_b64_tr_b16 v[104:105], v65 offset:25600
	ds_read_b64_tr_b16 v[106:107], v65 offset:26112
	v_add_f32_e32 v68, v82, v68
	v_add_f32_e32 v68, v83, v68
	v_add_f32_e32 v68, v84, v68
	v_add_f32_e32 v68, v85, v68
	v_cvt_pk_bf16_f32 v156, v80, v81
	v_cvt_pk_bf16_f32 v157, v82, v83
	s_waitcnt lgkmcnt(13)
	v_mfma_f32_32x32x16_bf16 v[128:143], v[188:191], v[152:155], v[128:143]
	ds_read_b64_tr_b16 v[80:81], v65 offset:29696
	ds_read_b64_tr_b16 v[82:83], v65 offset:30208
	v_add_f32_e32 v68, v86, v68
	v_add_f32_e32 v68, v87, v68
	v_add_f32_e32 v68, v88, v68
	v_add_f32_e32 v68, v89, v68
	v_cvt_pk_bf16_f32 v158, v84, v85
	v_cvt_pk_bf16_f32 v159, v86, v87
	s_waitcnt lgkmcnt(14)
	v_mfma_f32_32x32x16_bf16 v[112:127], v[184:187], v[152:155], v[112:127]
	ds_read_b64_tr_b16 v[84:85], v65 offset:33792
	ds_read_b64_tr_b16 v[86:87], v65 offset:34304
	v_add_f32_e32 v68, v90, v68
	v_add_f32_e32 v68, v91, v68
	v_add_f32_e32 v68, v92, v68
	v_add_f32_e32 v68, v93, v68
	v_cvt_pk_bf16_f32 v148, v88, v89
	v_cvt_pk_bf16_f32 v149, v90, v91
	s_waitcnt lgkmcnt(14)
	v_mfma_f32_32x32x16_bf16 v[128:143], v[180:183], v[144:147], v[128:143]
	ds_read_b64_tr_b16 v[88:89], v65 offset:37888
	ds_read_b64_tr_b16 v[90:91], v65 offset:38400
	v_add_f32_e32 v68, v94, v68
	v_add_f32_e32 v68, v95, v68
	v_cvt_pk_bf16_f32 v150, v92, v93
	v_cvt_pk_bf16_f32 v151, v94, v95
	v_mfma_f32_32x32x16_bf16 v[112:127], v[176:179], v[144:147], v[112:127]
	v_add_f32_e32 v64, v64, v68
	s_waitcnt lgkmcnt(14)
	v_mfma_f32_32x32x16_bf16 v[48:63], v[172:175], v[72:75], v[48:63]
	ds_read_b64_tr_b16 v[72:73], v65 offset:26624
	ds_read_b64_tr_b16 v[74:75], v65 offset:27136
	v_exp_f32_e32 v128, v128
	v_exp_f32_e32 v129, v129
	s_waitcnt lgkmcnt(14)
	v_mfma_f32_32x32x16_bf16 v[32:47], v[172:175], v[76:79], v[32:47]
	v_exp_f32_e32 v130, v130
	v_exp_f32_e32 v131, v131
	ds_read_b64_tr_b16 v[76:77], v65 offset:30720
	ds_read_b64_tr_b16 v[78:79], v65 offset:31232
	s_add_i32 s15, s27, s20
	s_mov_b32 m0, s15
	s_nop 0
	global_load_lds_dwordx4 v250, s[98:99]
	s_add_u32 s98, s98, 0x60000
	s_addc_u32 s99, s99, 0
	s_waitcnt lgkmcnt(14)
	v_mfma_f32_32x32x16_bf16 v[16:31], v[172:175], v[96:99], v[16:31]
	v_exp_f32_e32 v132, v132
	v_exp_f32_e32 v133, v133
	ds_read_b64_tr_b16 v[92:93], v65 offset:34816
	ds_read_b64_tr_b16 v[94:95], v65 offset:35328
	s_waitcnt lgkmcnt(14)
	v_mfma_f32_32x32x16_bf16 v[0:15], v[172:175], v[100:103], v[0:15]
	v_exp_f32_e32 v134, v134
	v_exp_f32_e32 v135, v135
	ds_read_b64_tr_b16 v[96:97], v65 offset:38912
	ds_read_b64_tr_b16 v[98:99], v65 offset:39424
	s_waitcnt lgkmcnt(14)
	v_mfma_f32_32x32x16_bf16 v[48:63], v[164:167], v[104:107], v[48:63]
	v_exp_f32_e32 v136, v136
	v_exp_f32_e32 v137, v137
	ds_read_b64_tr_b16 v[100:101], v65 offset:27648
	ds_read_b64_tr_b16 v[102:103], v65 offset:28160
	s_lshl_b32 s15, s28, 1
	s_add_i32 s15, s15, s21
	s_mov_b32 m0, s15
	s_nop 0
	global_load_lds_dwordx4 v251, s[100:101]
	s_waitcnt lgkmcnt(14)
	v_mfma_f32_32x32x16_bf16 v[32:47], v[164:167], v[80:83], v[32:47]
	v_exp_f32_e32 v138, v138
	v_exp_f32_e32 v139, v139
	ds_read_b64_tr_b16 v[80:81], v65 offset:31744
	ds_read_b64_tr_b16 v[82:83], v65 offset:32256
	s_waitcnt lgkmcnt(14)
	v_mfma_f32_32x32x16_bf16 v[16:31], v[164:167], v[84:87], v[16:31]
	v_exp_f32_e32 v140, v140
	v_exp_f32_e32 v141, v141
	ds_read_b64_tr_b16 v[84:85], v65 offset:35840
	ds_read_b64_tr_b16 v[86:87], v65 offset:36352
	s_waitcnt lgkmcnt(14)
	v_mfma_f32_32x32x16_bf16 v[0:15], v[164:167], v[88:91], v[0:15]
	v_exp_f32_e32 v142, v142
	v_exp_f32_e32 v143, v143
	ds_read_b64_tr_b16 v[88:89], v65 offset:39936
	ds_read_b64_tr_b16 v[90:91], v65 offset:40448
	s_lshl_b32 s15, s28, 1
	s_add_i32 s15, s15, s21
	s_addk_i32 s15, 0x1f80
	s_mov_b32 m0, s15
	s_nop 0
	global_load_lds_dwordx4 v251, s[100:101] offset:128
	s_add_u32 s100, s100, 0x60000
	s_addc_u32 s101, s101, 0
	s_waitcnt lgkmcnt(14)
	v_mfma_f32_32x32x16_bf16 v[48:63], v[156:159], v[72:75], v[48:63]
	v_exp_f32_e32 v112, v112
	v_exp_f32_e32 v113, v113
	s_waitcnt lgkmcnt(12)
	v_mfma_f32_32x32x16_bf16 v[32:47], v[156:159], v[76:79], v[32:47]
	v_exp_f32_e32 v114, v114
	v_exp_f32_e32 v115, v115
	v_add_u32_e32 v65, s37, v241
	ds_read_b128 v[72:75], v65
	ds_read_b128 v[76:79], v65 offset:512
	s_waitcnt lgkmcnt(12)
	v_mfma_f32_32x32x16_bf16 v[16:31], v[156:159], v[92:95], v[16:31]
	v_exp_f32_e32 v116, v116
	v_exp_f32_e32 v117, v117
	ds_read_b128 v[176:179], v65 offset:2048
	ds_read_b128 v[180:183], v65 offset:2560
	s_waitcnt lgkmcnt(12)
	v_mfma_f32_32x32x16_bf16 v[0:15], v[156:159], v[96:99], v[0:15]
	v_exp_f32_e32 v118, v118
	v_exp_f32_e32 v119, v119
	ds_read_b128 v[184:187], v65 offset:4096
	ds_read_b128 v[188:191], v65 offset:4608
	s_waitcnt lgkmcnt(12)
	v_mfma_f32_32x32x16_bf16 v[48:63], v[148:151], v[100:103], v[48:63]
	v_exp_f32_e32 v120, v120
	v_exp_f32_e32 v121, v121
	ds_read_b128 v[192:195], v65 offset:6144
	ds_read_b128 v[196:199], v65 offset:6656
	s_waitcnt lgkmcnt(12)
	v_mfma_f32_32x32x16_bf16 v[32:47], v[148:151], v[80:83], v[32:47]
	v_exp_f32_e32 v122, v122
	v_exp_f32_e32 v123, v123
	s_waitcnt lgkmcnt(10)
	v_mfma_f32_32x32x16_bf16 v[16:31], v[148:151], v[84:87], v[16:31]
	v_exp_f32_e32 v124, v124
	v_exp_f32_e32 v125, v125
	s_waitcnt lgkmcnt(8)
	v_mfma_f32_32x32x16_bf16 v[0:15], v[148:151], v[88:91], v[0:15]
	v_exp_f32_e32 v126, v126
	v_exp_f32_e32 v127, v127
	s_waitcnt vmcnt(3) lgkmcnt(0)
	s_barrier
	s_add_i32 s15, s28, 0x2000
	s_cmpk_lg_i32 s28, 0x4000
	s_cselect_b32 s27, s15, 0
	v_lshl_add_u32 v65, s14, 1, v239
	ds_read_b64_tr_b16 v[200:201], v65 offset:24576
	ds_read_b64_tr_b16 v[202:203], v65 offset:25088
	s_waitcnt lgkmcnt(9)
	v_mfma_f32_32x32x16_bf16 v[96:111], v[72:75], v[168:171], 0
	v_add_f32_e32 v80, v128, v129
	v_add_f32_e32 v80, v130, v80
	v_add_f32_e32 v80, v131, v80
	v_add_f32_e32 v80, v132, v80
	v_add_f32_e32 v80, v133, v80
	v_cvt_pk_bf16_f32 v172, v128, v129
	v_cvt_pk_bf16_f32 v173, v130, v131
	ds_read_b64_tr_b16 v[72:73], v65 offset:28672
	ds_read_b64_tr_b16 v[74:75], v65 offset:29184
	v_add_f32_e32 v80, v134, v80
	v_add_f32_e32 v80, v135, v80
	v_add_f32_e32 v80, v136, v80
	v_add_f32_e32 v128, v137, v80
	s_waitcnt lgkmcnt(10)
	v_mfma_f32_32x32x16_bf16 v[80:95], v[76:79], v[168:171], 0
	v_cvt_pk_bf16_f32 v174, v132, v133
	v_cvt_pk_bf16_f32 v175, v134, v135
	ds_read_b64_tr_b16 v[76:77], v65 offset:32768
	ds_read_b64_tr_b16 v[78:79], v65 offset:33280
	s_waitcnt lgkmcnt(11)
	v_mfma_f32_32x32x16_bf16 v[96:111], v[176:179], v[160:163], v[96:111]
	v_add_f32_e32 v128, v138, v128
	v_add_f32_e32 v128, v139, v128
	v_add_f32_e32 v128, v140, v128
	v_add_f32_e32 v132, v141, v128
	v_cvt_pk_bf16_f32 v164, v136, v137
	v_cvt_pk_bf16_f32 v165, v138, v139
	ds_read_b64_tr_b16 v[128:129], v65 offset:36864
	ds_read_b64_tr_b16 v[130:131], v65 offset:37376
	s_waitcnt lgkmcnt(12)
	v_mfma_f32_32x32x16_bf16 v[80:95], v[180:183], v[160:163], v[80:95]
	v_add_f32_e32 v132, v142, v132
	v_add_f32_e32 v132, v143, v132
	v_add_f32_e32 v132, v112, v132
	v_add_f32_e32 v136, v113, v132
	v_cvt_pk_bf16_f32 v166, v140, v141
	v_cvt_pk_bf16_f32 v167, v142, v143
	ds_read_b64_tr_b16 v[132:133], v65 offset:25600
	ds_read_b64_tr_b16 v[134:135], v65 offset:26112
	s_waitcnt lgkmcnt(13)
	v_mfma_f32_32x32x16_bf16 v[96:111], v[184:187], v[152:155], v[96:111]
	v_add_f32_e32 v136, v114, v136
	v_add_f32_e32 v136, v115, v136
	v_add_f32_e32 v136, v116, v136
	v_add_f32_e32 v136, v117, v136
	v_cvt_pk_bf16_f32 v156, v112, v113
	v_cvt_pk_bf16_f32 v157, v114, v115
	ds_read_b64_tr_b16 v[112:113], v65 offset:29696
	ds_read_b64_tr_b16 v[114:115], v65 offset:30208
	s_waitcnt lgkmcnt(14)
	v_mfma_f32_32x32x16_bf16 v[80:95], v[188:191], v[152:155], v[80:95]
	v_add_f32_e32 v136, v118, v136
	v_add_f32_e32 v136, v119, v136
	v_add_f32_e32 v136, v120, v136
	v_add_f32_e32 v136, v121, v136
	v_cvt_pk_bf16_f32 v158, v116, v117
	v_cvt_pk_bf16_f32 v159, v118, v119
	ds_read_b64_tr_b16 v[116:117], v65 offset:33792
	ds_read_b64_tr_b16 v[118:119], v65 offset:34304
	s_waitcnt lgkmcnt(14)
	v_mfma_f32_32x32x16_bf16 v[96:111], v[192:195], v[144:147], v[96:111]
	v_add_f32_e32 v136, v122, v136
	v_add_f32_e32 v136, v123, v136
	v_add_f32_e32 v136, v124, v136
	v_add_f32_e32 v136, v125, v136
	v_cvt_pk_bf16_f32 v148, v120, v121
	v_cvt_pk_bf16_f32 v149, v122, v123
	ds_read_b64_tr_b16 v[120:121], v65 offset:37888
	ds_read_b64_tr_b16 v[122:123], v65 offset:38400
	v_mfma_f32_32x32x16_bf16 v[80:95], v[196:199], v[144:147], v[80:95]
	v_add_f32_e32 v136, v126, v136
	v_add_f32_e32 v136, v127, v136
	v_cvt_pk_bf16_f32 v150, v124, v125
	v_cvt_pk_bf16_f32 v151, v126, v127
	v_add_f32_e32 v64, v64, v136
	s_add_i32 s35, s35, 2
	s_waitcnt lgkmcnt(14)
	v_mfma_f32_32x32x16_bf16 v[48:63], v[172:175], v[200:203], v[48:63]
	ds_read_b64_tr_b16 v[68:69], v65 offset:26624
	ds_read_b64_tr_b16 v[70:71], v65 offset:27136
	v_exp_f32_e32 v96, v96
	v_exp_f32_e32 v97, v97
	s_waitcnt lgkmcnt(14)
	v_mfma_f32_32x32x16_bf16 v[32:47], v[172:175], v[72:75], v[32:47]
	v_exp_f32_e32 v98, v98
	v_exp_f32_e32 v99, v99
	ds_read_b64_tr_b16 v[72:73], v65 offset:30720
	ds_read_b64_tr_b16 v[74:75], v65 offset:31232
	s_add_i32 s24, s28, s20
	s_mov_b32 m0, s24
	s_nop 0
	global_load_lds_dwordx4 v250, s[98:99]
	s_add_u32 s98, s98, 0x60000
	s_addc_u32 s99, s99, 0
	s_waitcnt lgkmcnt(14)
; #define WAIT_BAR(N) asm volatile("s_waitcnt vmcnt(" #N ") lgkmcnt(0)\n\ts_barrier":::"memory")
;   #define ROT() do{sl_prev=sl_cur;sl_cur=sl_next;sl_next=(sl_next==(NSLOT-1)*SLOTB)?0:sl_next+SLOTB;}while(0)
; template<int DUMMY> __device__ __forceinline__ void attn_pass2(const bf16*Qh,const bf16*__restrict__ Kh,const bf16*__restrict__ Vh,const int q0,char*shm,f32x16 (&o)[4]){
;     ...
;   int t=1;
;     ...
;   for(;t+5<NT;t+=2){
;     STEP(pB0,pB1,pA0,pA1,t,true,true,true);     WAIT_BAR(3); ROT();
;     STEP(pA0,pA1,pB0,pB1,t+1,true,true,true);   WAIT_BAR(3); ROT();
;   }
;     ...
;   for(;t+1<NT;t+=2){
	v_mfma_f32_32x32x16_bf16 v[16:31], v[172:175], v[76:79], v[16:31]
	v_exp_f32_e32 v100, v100
	v_exp_f32_e32 v101, v101
	ds_read_b64_tr_b16 v[76:77], v65 offset:34816
	ds_read_b64_tr_b16 v[78:79], v65 offset:35328
	s_waitcnt lgkmcnt(14)
	v_mfma_f32_32x32x16_bf16 v[0:15], v[172:175], v[128:131], v[0:15]
	v_exp_f32_e32 v102, v102
	v_exp_f32_e32 v103, v103
	ds_read_b64_tr_b16 v[124:125], v65 offset:38912
	ds_read_b64_tr_b16 v[126:127], v65 offset:39424
	s_waitcnt lgkmcnt(14)
	v_mfma_f32_32x32x16_bf16 v[48:63], v[164:167], v[132:135], v[48:63]
	v_exp_f32_e32 v104, v104
	v_exp_f32_e32 v105, v105
	ds_read_b64_tr_b16 v[128:129], v65 offset:27648
	ds_read_b64_tr_b16 v[130:131], v65 offset:28160
	s_lshl_b32 s24, s27, 1
	s_add_i32 s24, s24, s21
	s_mov_b32 m0, s24
	s_nop 0
	global_load_lds_dwordx4 v251, s[100:101]
	s_waitcnt lgkmcnt(14)
	v_mfma_f32_32x32x16_bf16 v[32:47], v[164:167], v[112:115], v[32:47]
	v_exp_f32_e32 v106, v106
	v_exp_f32_e32 v107, v107
	ds_read_b64_tr_b16 v[112:113], v65 offset:31744
	ds_read_b64_tr_b16 v[114:115], v65 offset:32256
	s_waitcnt lgkmcnt(14)
	v_mfma_f32_32x32x16_bf16 v[16:31], v[164:167], v[116:119], v[16:31]
	v_exp_f32_e32 v108, v108
	v_exp_f32_e32 v109, v109
	ds_read_b64_tr_b16 v[116:117], v65 offset:35840
	ds_read_b64_tr_b16 v[118:119], v65 offset:36352
	s_waitcnt lgkmcnt(14)
	v_mfma_f32_32x32x16_bf16 v[0:15], v[164:167], v[120:123], v[0:15]
	v_exp_f32_e32 v110, v110
	v_exp_f32_e32 v111, v111
	ds_read_b64_tr_b16 v[120:121], v65 offset:39936
	ds_read_b64_tr_b16 v[122:123], v65 offset:40448
	s_lshl_b32 s24, s27, 1
	s_add_i32 s24, s24, s21
	s_addk_i32 s24, 0x1f80
	s_mov_b32 m0, s24
	s_nop 0
	global_load_lds_dwordx4 v251, s[100:101] offset:128
	s_add_u32 s100, s100, 0x60000
	s_addc_u32 s101, s101, 0
	s_waitcnt lgkmcnt(14)
	v_mfma_f32_32x32x16_bf16 v[48:63], v[156:159], v[68:71], v[48:63]
	v_exp_f32_e32 v80, v80
	v_exp_f32_e32 v81, v81
	s_waitcnt lgkmcnt(12)
	v_mfma_f32_32x32x16_bf16 v[32:47], v[156:159], v[72:75], v[32:47]
	v_exp_f32_e32 v82, v82
	v_exp_f32_e32 v83, v83
	v_add_u32_e32 v65, s27, v241
	ds_read_b128 v[204:207], v65
	ds_read_b128 v[200:203], v65 offset:512
	s_waitcnt lgkmcnt(12)
	v_mfma_f32_32x32x16_bf16 v[16:31], v[156:159], v[76:79], v[16:31]
	v_exp_f32_e32 v84, v84
	v_exp_f32_e32 v85, v85
	ds_read_b128 v[196:199], v65 offset:2048
	ds_read_b128 v[192:195], v65 offset:2560
	s_waitcnt lgkmcnt(12)
	v_mfma_f32_32x32x16_bf16 v[0:15], v[156:159], v[124:127], v[0:15]
	v_exp_f32_e32 v86, v86
	v_exp_f32_e32 v87, v87
	ds_read_b128 v[188:191], v65 offset:4096
	ds_read_b128 v[184:187], v65 offset:4608
	s_waitcnt lgkmcnt(12)
	v_mfma_f32_32x32x16_bf16 v[48:63], v[148:151], v[128:131], v[48:63]
	v_exp_f32_e32 v88, v88
	v_exp_f32_e32 v89, v89
	ds_read_b128 v[180:183], v65 offset:6144
	ds_read_b128 v[176:179], v65 offset:6656
	s_waitcnt lgkmcnt(12)
	v_mfma_f32_32x32x16_bf16 v[32:47], v[148:151], v[112:115], v[32:47]
	v_exp_f32_e32 v90, v90
	v_exp_f32_e32 v91, v91
	s_waitcnt lgkmcnt(10)
	v_mfma_f32_32x32x16_bf16 v[16:31], v[148:151], v[116:119], v[16:31]
	v_exp_f32_e32 v92, v92
	v_exp_f32_e32 v93, v93
	s_waitcnt lgkmcnt(8)
	v_mfma_f32_32x32x16_bf16 v[0:15], v[148:151], v[120:123], v[0:15]
	v_exp_f32_e32 v94, v94
	v_exp_f32_e32 v95, v95
	s_add_i32 s14, s27, 0x2000
	s_cmpk_lg_i32 s27, 0x4000
	s_waitcnt vmcnt(3) lgkmcnt(0)
	s_barrier
	s_cselect_b32 s28, s14, 0
	s_add_u32 s56, s56, 0xc0000
	s_addc_u32 s57, s57, 0
	s_cmp_ge_i32 s35, s11
	s_mov_b32 s15, s37
	s_cbranch_scc0 .LBB0_304
	s_setprio 0
	s_ashr_i32 s11, s10, 31
	s_add_i32 s14, s35, 1
	s_cmp_lt_i32 s14, s25
	s_cbranch_scc1 .LBB0_315
